# selected-branch tile: 15-register bias broadcast done with one v_mov_b32 and seven v_mov_b64
# speedup vs baseline: 1.0031x; 1.0031x over previous
; #define LAS __attribute__((address_space(3)))
; #define MFMA32(a, b, c) __builtin_amdgcn_mfma_f32_32x32x16_bf16((a), (b), (c), 0, 0, 0)
; template <int BR>
; DI void attn_branch(const AttnCtx& c, unsigned long long tmask, const bf16_t* kbase, size_t kpitch, const bf16_t* vbase, size_t vpitch, f32x16 (&o)[2], float& lsum) {
;     ...
;         if (BR == 2) mine = (c.mymask >> jc) & 1ull;
;         const bool wave_on = (BR == 2 ? (__ballot(mine) != 0ull) : true) && !c.nocompute;
;         if (wave_on) {
;             const float sbias = (BR == 2 && !mine) ? -1e30f : 0.f;
;             bool interior;
;             if (BR <= 1) interior = jc * 64 + 64 <= c.ncvmin;
;             else if (BR == 2) interior = jc * 64 + 63 <= c.tw;
;             else interior = (jc * 64 + 63 <= c.tw) && (jc * 64 > c.tw + 31 - 512);
;             if (interior) {
;                 f32x16 s0, s1;
; #pragma unroll
;                 for (int i = 0; i < 16; ++i) { s0[i] = sbias; s1[i] = sbias; }
; #pragma unroll
;                 for (int st = 0; st < 4; ++st) {
;                     const bf16x8 kf0 = *(const LAS bf16x8*)(Ks + c.qi * 72 + 16 * st + 8 * c.hi), kf1 = *(const LAS bf16x8*)(Ks + (32 + c.qi) * 72 + 16 * st + 8 * c.hi);
;                     s0 = MFMA32(kf0, c.q[st], s0); s1 = MFMA32(kf1, c.q[st], s1);
;                 }
;                 float p0[16], p1[16];
; #pragma unroll
;                 for (int i = 0; i < 16; ++i) { p0[i] = __builtin_amdgcn_exp2f(s0[i]); p1[i] = __builtin_amdgcn_exp2f(s1[i]); }
;                 {
;                     float l0 = 0.f, l1 = 0.f;
; #pragma unroll
;                     for (int i = 0; i < 16; ++i) { l0 += p0[i]; l1 += p1[i]; }
;                     lsum += l0 + l1;
;                 }
;                 if (BR == 1) {
; #pragma unroll
;                     for (int gq = 0; gq < 4; ++gq) {
;                         const int jj = jc * 16 + gq * 2 + c.hi;
;                         __hip_atomic_fetch_add(c.impw + jj, (p0[4 * gq] + p0[4 * gq + 1]) + (p0[4 * gq + 2] + p0[4 * gq + 3]), __ATOMIC_RELAXED, __HIP_MEMORY_SCOPE_WORKGROUP);
;                         __hip_atomic_fetch_add(c.impw + jj + 1, p0[4 * gq + 3], __ATOMIC_RELAXED, __HIP_MEMORY_SCOPE_WORKGROUP);
;                     }
; #pragma unroll
;                     for (int gq = 0; gq < 4; ++gq) {
;                         const int jj = jc * 16 + 8 + gq * 2 + c.hi;
.LBB0_377:
	s_waitcnt lgkmcnt(0)
	s_barrier
	v_lshrrev_b64 v[64:65], s10, v[106:107]
	v_and_b32_e32 v64, 1, v64
	v_cmp_eq_u32_e64 s[0:1], 1, v64
	v_cmp_ne_u32_e32 vcc, 0, v64
	s_cbranch_vccz .LBB0_387
	s_lshl_b32 s15, s10, 6
	v_cndmask_b32_e64 v64, v193, 0, s[0:1]
	s_or_b32 s0, s15, 63
	v_cmp_le_i32_e32 vcc, s0, v171
	s_and_saveexec_b64 s[0:1], vcc
	s_xor_b64 s[0:1], exec, s[0:1]
	s_cbranch_execz .LBB0_380
	v_lshlrev_b32_e32 v80, 1, v170
	v_add3_u32 v109, s14, v185, v80
	ds_read_b128 v[212:215], v109
	ds_read_b128 v[216:219], v109 offset:4608
	ds_read_b128 v[220:223], v109 offset:32
	ds_read_b128 v[224:227], v109 offset:4640
	ds_read_b128 v[228:231], v109 offset:64
	ds_read_b128 v[232:235], v109 offset:4672
	ds_read_b128 v[236:239], v109 offset:96
	ds_read_b128 v[240:243], v109 offset:4704
	v_mov_b32_e32 v65, v64
	v_mov_b64_e32 v[66:67], v[64:65]
	v_mov_b64_e32 v[68:69], v[64:65]
	v_mov_b64_e32 v[70:71], v[64:65]
	v_mov_b64_e32 v[72:73], v[64:65]
	v_mov_b64_e32 v[74:75], v[64:65]
	v_mov_b64_e32 v[76:77], v[64:65]
	v_mov_b64_e32 v[78:79], v[64:65]
	s_nop 0
	s_waitcnt lgkmcnt(7)
	v_mfma_f32_32x32x16_bf16 v[80:95], v[212:215], v[130:133], v[64:79]
	s_waitcnt lgkmcnt(5)
	v_mfma_f32_32x32x16_bf16 v[80:95], v[220:223], v[134:137], v[80:95]
	s_waitcnt lgkmcnt(3)
	v_mfma_f32_32x32x16_bf16 v[80:95], v[228:231], v[138:141], v[80:95]
	s_waitcnt lgkmcnt(1)
	v_mfma_f32_32x32x16_bf16 v[80:95], v[236:239], v[142:145], v[80:95]
	s_waitcnt lgkmcnt(0)
	v_mfma_f32_32x32x16_bf16 v[64:79], v[216:219], v[130:133], v[64:79]
	v_mfma_f32_32x32x16_bf16 v[64:79], v[224:227], v[134:137], v[64:79]
	s_nop 9
	v_exp_f32_e32 v80, v80
	v_exp_f32_e32 v81, v81
	v_exp_f32_e32 v82, v82
	v_mfma_f32_32x32x16_bf16 v[64:79], v[232:235], v[138:141], v[64:79]
	v_exp_f32_e32 v83, v83
	v_exp_f32_e32 v84, v84
	v_exp_f32_e32 v85, v85
	v_mfma_f32_32x32x16_bf16 v[64:79], v[240:243], v[142:145], v[64:79]
	v_add3_u32 v251, s14, v186, v170
	v_add_u32_e32 v255, 0x2000, v251
	v_add_u32_e32 v251, 0x3000, v251
	ds_read2_b64 v[212:215], v255 offset0:128 offset1:130
	ds_read2_b64 v[216:219], v251 offset0:160 offset1:162
	ds_read2_b64 v[220:223], v255 offset0:132 offset1:134
	ds_read2_b64 v[224:227], v251 offset0:164 offset1:166
	ds_read2_b64 v[228:231], v255 offset0:136 offset1:138
	ds_read2_b64 v[232:235], v251 offset0:168 offset1:170
	ds_read2_b64 v[236:239], v255 offset0:140 offset1:142
	ds_read2_b64 v[240:243], v251 offset0:172 offset1:174
	v_exp_f32_e32 v86, v86
	v_exp_f32_e32 v87, v87
	v_exp_f32_e32 v88, v88
	v_exp_f32_e32 v89, v89
	v_exp_f32_e32 v90, v90
	v_exp_f32_e32 v91, v91
	v_exp_f32_e32 v92, v92
	v_exp_f32_e32 v93, v93
	v_exp_f32_e32 v94, v94
	v_exp_f32_e32 v95, v95
	v_pk_add_f32 v[252:253], v[80:81], v[82:83]
	v_pk_add_f32 v[254:255], v[84:85], v[86:87]
	v_pk_add_f32 v[252:253], v[88:89], v[252:253]
	v_pk_add_f32 v[254:255], v[90:91], v[254:255]
	v_pk_add_f32 v[252:253], v[92:93], v[252:253]
	v_pk_add_f32 v[254:255], v[94:95], v[254:255]
	v_cvt_pk_bf16_f32 v116, v80, v81
	v_cvt_pk_bf16_f32 v117, v82, v83
	v_cvt_pk_bf16_f32 v118, v84, v85
	v_cvt_pk_bf16_f32 v119, v86, v87
	v_cvt_pk_bf16_f32 v120, v88, v89
	v_cvt_pk_bf16_f32 v121, v90, v91
	v_cvt_pk_bf16_f32 v122, v92, v93
	v_cvt_pk_bf16_f32 v123, v94, v95
	s_waitcnt lgkmcnt(0)
	v_mfma_f32_32x32x16_bf16 v[48:63], v[212:215], v[116:119], v[48:63]
	v_exp_f32_e32 v64, v64
	v_exp_f32_e32 v65, v65
	v_exp_f32_e32 v66, v66
	v_exp_f32_e32 v67, v67
	v_mfma_f32_32x32x16_bf16 v[32:47], v[216:219], v[116:119], v[32:47]
	v_exp_f32_e32 v68, v68
	v_exp_f32_e32 v69, v69
	v_exp_f32_e32 v70, v70
	v_exp_f32_e32 v71, v71
	v_mfma_f32_32x32x16_bf16 v[48:63], v[220:223], v[120:123], v[48:63]
	v_exp_f32_e32 v72, v72
	v_exp_f32_e32 v73, v73
	v_exp_f32_e32 v74, v74
	v_exp_f32_e32 v75, v75
	v_mfma_f32_32x32x16_bf16 v[32:47], v[224:227], v[120:123], v[32:47]
	v_exp_f32_e32 v76, v76
	v_exp_f32_e32 v77, v77
	v_exp_f32_e32 v78, v78
	v_exp_f32_e32 v79, v79
	v_pk_add_f32 v[252:253], v[64:65], v[252:253]
	v_pk_add_f32 v[254:255], v[66:67], v[254:255]
	v_pk_add_f32 v[252:253], v[68:69], v[252:253]
	v_pk_add_f32 v[254:255], v[70:71], v[254:255]
	v_pk_add_f32 v[252:253], v[72:73], v[252:253]
	v_pk_add_f32 v[254:255], v[74:75], v[254:255]
	v_pk_add_f32 v[252:253], v[76:77], v[252:253]
	v_pk_add_f32 v[254:255], v[78:79], v[254:255]
	v_cvt_pk_bf16_f32 v124, v64, v65
	v_cvt_pk_bf16_f32 v125, v66, v67
	v_cvt_pk_bf16_f32 v126, v68, v69
	v_cvt_pk_bf16_f32 v127, v70, v71
	v_pk_add_f32 v[252:253], v[252:253], v[254:255]
	v_cvt_pk_bf16_f32 v80, v72, v73
	v_cvt_pk_bf16_f32 v81, v74, v75
	v_cvt_pk_bf16_f32 v82, v76, v77
	v_cvt_pk_bf16_f32 v83, v78, v79
	v_add_f32_e32 v252, v252, v253
	v_add_f32_e32 v175, v175, v252
	v_mfma_f32_32x32x16_bf16 v[48:63], v[228:231], v[124:127], v[48:63]
	v_mfma_f32_32x32x16_bf16 v[32:47], v[232:235], v[124:127], v[32:47]
	v_mfma_f32_32x32x16_bf16 v[48:63], v[236:239], v[80:83], v[48:63]
	v_mfma_f32_32x32x16_bf16 v[32:47], v[240:243], v[80:83], v[32:47]
